# T1: GEMM1 tail-quadrant K-loop: A-fragment LDS reads of row group m+1 issued before the MFMAs of row group m (second fragment set v[72:79])
# baseline (speedup 1.0000x reference)
; #define LAS __attribute__((address_space(3)))
; __device__ __forceinline__ void gemm1_tail_quadrant(LAS unsigned char* lds, const f16* A, const f16* Bt, unsigned char* ws, int pm, int pn, int ai, int bj) {
;     ...
;     for (int t = 0; t < NT; ++t) {
;         if (t <= NT - 3) asm volatile("s_waitcnt vmcnt(8)" ::: "memory"); else if (t == NT - 2) asm volatile("s_waitcnt vmcnt(4)" ::: "memory"); else asm volatile("s_waitcnt vmcnt(0)" ::: "memory");
;         __builtin_amdgcn_s_barrier();
;         if (t + 3 < NT) QSTAGE((t + 3) & 3, t + 3);
;         LAS unsigned char* sl = lds + (t & 3) * 32768;
;         f16x8 At[4][2], Bf[2][2];
; #pragma unroll
;         for (int m = 0; m < 4; ++m)
; #pragma unroll
;             for (int k = 0; k < 2; ++k) At[m][k] = *(const LAS f16x8*)(sl + aoff + m * 2048 + k * 1024);
; #pragma unroll
;         for (int n = 0; n < 2; ++n)
; #pragma unroll
;             for (int k = 0; k < 2; ++k) Bf[n][k] = *(const LAS f16x8*)(sl + 16384 + boff + n * 2048 + k * 1024);
; #pragma unroll
;         for (int m = 0; m < 4; ++m)
; #pragma unroll
;             for (int n = 0; n < 2; ++n)
; #pragma unroll
;                 for (int k = 0; k < 2; ++k) acc[m][n] = __builtin_amdgcn_mfma_f32_16x16x32_f16(Bf[n][k], At[m][k], acc[m][n], 0, 0, 0);
.LBB0_327:
	s_add_i32 s6, s37, 0xfffe8000
	s_and_b32 s6, s6, 0x18000
	s_add_i32 s6, s6, 0
	s_add_i32 s7, s35, s6
	v_add_u32_e32 v66, s7, v45
	s_add_i32 s6, s34, s6
	v_add_u32_e32 v70, s6, v45
	ds_read_b128 v[46:49], v66 offset:16384
	ds_read_b128 v[50:53], v70
	ds_read_b128 v[62:65], v66 offset:18432
	ds_read_b128 v[54:57], v70 offset:1024
	ds_read_b128 v[58:61], v66 offset:17408
	ds_read_b128 v[66:69], v66 offset:19456
	ds_read_b128 v[72:75], v70 offset:2048
	ds_read_b128 v[76:79], v70 offset:3072
	s_waitcnt lgkmcnt(2)
	v_mfma_f32_16x16x32_f16 v[34:37], v[62:65], v[50:53], v[34:37]
	s_add_i32 s36, s36, 1
	s_add_i32 s37, s37, 0x8000
	s_add_u32 s4, s4, 0x80
	v_mfma_f32_16x16x32_f16 v[38:41], v[46:49], v[50:53], v[38:41]
	s_addc_u32 s5, s5, 0
	s_cmpk_lg_i32 s4, 0x800
	v_mfma_f32_16x16x32_f16 v[38:41], v[58:61], v[54:57], v[38:41]
	v_mfma_f32_16x16x32_f16 v[34:37], v[66:69], v[54:57], v[34:37]
	ds_read_b128 v[50:53], v70 offset:4096
	ds_read_b128 v[54:57], v70 offset:5120
	s_waitcnt lgkmcnt(2)
	v_mfma_f32_16x16x32_f16 v[26:29], v[46:49], v[72:75], v[26:29]
	v_mfma_f32_16x16x32_f16 v[18:21], v[62:65], v[72:75], v[18:21]
	v_mfma_f32_16x16x32_f16 v[26:29], v[58:61], v[76:79], v[26:29]
	v_mfma_f32_16x16x32_f16 v[18:21], v[66:69], v[76:79], v[18:21]
	ds_read_b128 v[72:75], v70 offset:6144
	ds_read_b128 v[76:79], v70 offset:7168
	s_waitcnt lgkmcnt(2)
	v_mfma_f32_16x16x32_f16 v[14:17], v[46:49], v[50:53], v[14:17]
	v_mfma_f32_16x16x32_f16 v[10:13], v[62:65], v[50:53], v[10:13]
	v_mfma_f32_16x16x32_f16 v[14:17], v[58:61], v[54:57], v[14:17]
	v_mfma_f32_16x16x32_f16 v[10:13], v[66:69], v[54:57], v[10:13]
	s_waitcnt lgkmcnt(0)
	v_mfma_f32_16x16x32_f16 v[2:5], v[46:49], v[72:75], v[2:5]
	v_mfma_f32_16x16x32_f16 v[6:9], v[62:65], v[72:75], v[6:9]
	v_mfma_f32_16x16x32_f16 v[2:5], v[58:61], v[76:79], v[2:5]
	v_mfma_f32_16x16x32_f16 v[6:9], v[66:69], v[76:79], v[6:9]
	s_cbranch_scc0 .LBB0_319
